# fourier mid-row moved from the head of P3 into P4, its loads overlapped with the chunk-state scan
# baseline (speedup 1.0000x reference)
; __device__ __forceinline__ int otid(int wv) { int ln; asm volatile("v_mbcnt_lo_u32_b32 %0, -1, 0\n\tv_mbcnt_hi_u32_b32 %0, -1, %0" : "=v"(ln)); return wv * 64 + ln; }
; __device__ __forceinline__ void fourier_mid_row(int wv, const Params& p) {
;     const int tid = otid(wv), lane = tid & 63, gw = blockIdx.x * 8 + (tid >> 6), nw = gridDim.x * 8;
;     const bf16_t* TLAT = (const bf16_t*)(p.ws + OFF_TLAT); bf16_t* PQ = (bf16_t*)(p.ws + OFF_PQ);
;     for (int pr = gw; pr < 2048; pr += nw) { const int bt = pr >> 8, ch = pr & 255;
;         const bf16_t* src = TLAT + ((size_t)bt * 1024 + ch) * 2048 + lane * 32; float acc = 0.f;
.Lgb_end_2:
.LBB0_587:
	s_or_b64 exec, exec, s[6:7]
	s_mov_b64 s[4:5], s[90:91]
	s_waitcnt lgkmcnt(0)
	s_barrier
	v_mbcnt_lo_u32_b32 v0, -1, 0
	v_mbcnt_hi_u32_b32 v0, -1, v0
	v_readlane_b32 s0, v254, 30
	v_add_u32_e32 v2, s89, v0
	v_ashrrev_i32_e32 v2, 6, v2
	v_add_u32_e32 v6, s0, v2
	s_movk_i32 s0, 0x800
	v_cmp_gt_i32_e32 vcc, s0, v6
	s_and_saveexec_b64 s[6:7], vcc
	s_branch .LBB0_592
	s_load_dwordx2 s[0:1], s[4:5], 0xa8
	v_and_b32_e32 v2, 63, v0
	v_lshlrev_b32_e32 v0, 5, v2
	v_cmp_eq_u32_e64 s[10:11], 0, v2
	v_lshlrev_b32_e32 v2, 2, v2
	s_waitcnt lgkmcnt(0)
	s_add_u32 s8, s0, 0x6320000
	s_addc_u32 s9, s1, 0
	s_add_u32 s12, s0, 0x8720000
	s_addc_u32 s13, s1, 0
	v_xor_b32_e32 v7, 0x80, v2
	v_xor_b32_e32 v8, 64, v2
	v_xor_b32_e32 v9, 32, v2
	v_xor_b32_e32 v10, 16, v2
	v_xor_b32_e32 v11, 8, v2
	v_xor_b32_e32 v12, 4, v2
	s_mov_b64 s[14:15], 0
	v_lshlrev_b32_e32 v2, 1, v0
	s_branch .LBB0_590

; __device__ __forceinline__ int otid(int wv) { int ln; asm volatile("v_mbcnt_lo_u32_b32 %0, -1, 0\n\tv_mbcnt_hi_u32_b32 %0, -1, %0" : "=v"(ln)); return wv * 64 + ln; }
; __device__ __forceinline__ void fourier_mid_row(int wv, const Params& p) {
;     const int tid = otid(wv), lane = tid & 63, gw = blockIdx.x * 8 + (tid >> 6), nw = gridDim.x * 8;
;     const bf16_t* TLAT = (const bf16_t*)(p.ws + OFF_TLAT); bf16_t* PQ = (bf16_t*)(p.ws + OFF_PQ);
;     for (int pr = gw; pr < 2048; pr += nw) { const int bt = pr >> 8, ch = pr & 255;
;         const bf16_t* src = TLAT + ((size_t)bt * 1024 + ch) * 2048 + lane * 32; float acc = 0.f;
; #pragma unroll
;         for (int j = 0; j < 4; ++j) { const u32x4 w = *(const u32x4*)(src + j * 8);
.Lgb_done_3:
.LBB0_882:
	s_or_b64 exec, exec, s[6:7]
	s_mov_b64 s[4:5], s[90:91]
	s_waitcnt lgkmcnt(0)
	s_barrier
	v_mbcnt_lo_u32_b32 v176, -1, 0
	v_mbcnt_hi_u32_b32 v176, -1, v176
	v_readlane_b32 s0, v254, 30
	v_add_u32_e32 v177, s89, v176
	v_ashrrev_i32_e32 v177, 6, v177
	s_load_dwordx2 s[12:13], s[90:91], 0xa8
	v_add_u32_e32 v177, s0, v177
	v_lshrrev_b32_e32 v178, 8, v177
	v_and_b32_e32 v179, 0xff, v177
	v_lshl_add_u32 v178, v178, 10, v179
	v_lshlrev_b32_e32 v178, 12, v178
	v_lshl_add_u32 v178, v176, 6, v178
	v_add_u32_e32 v178, 0x6320000, v178
	s_waitcnt lgkmcnt(0)
	global_load_dwordx4 v[180:183], v178, s[12:13] offset:48
	global_load_dwordx4 v[184:187], v178, s[12:13] offset:32
	global_load_dwordx4 v[188:191], v178, s[12:13] offset:16
	global_load_dwordx4 v[192:195], v178, s[12:13]
	v_mbcnt_lo_u32_b32 v0, -1, 0
	v_mbcnt_hi_u32_b32 v0, -1, v0
	v_readlane_b32 s0, v254, 59
	s_nop 1
	v_add_u32_e32 v0, s0, v0
	s_mov_b32 s0, 0x24000
	v_cmp_gt_i32_e32 vcc, s0, v0
	s_and_saveexec_b64 s[6:7], vcc
	s_cbranch_execz .LBB0_887
	s_load_dwordx2 s[0:1], s[4:5], 0xa8
	s_mov_b64 s[12:13], 0
	s_waitcnt lgkmcnt(0)
	s_add_u32 s8, s0, 0x9920000
	s_addc_u32 s9, s1, 0
	s_add_u32 s10, s0, 0xad60000
	s_addc_u32 s11, s1, 0

; #define LAS __attribute__((address_space(3)))
; __device__ __forceinline__ bf16_t f2bf(float f) { unsigned u = __float_as_uint(f); u += 0x7FFFu + ((u >> 16) & 1u); return (bf16_t)(u >> 16); }
; __device__ __forceinline__ float bflo(unsigned w) { return __uint_as_float(w << 16); }
; __device__ __forceinline__ float bfhi(unsigned w) { return __uint_as_float(w & 0xffff0000u); }
; __device__ __forceinline__ int otid(int wv) { int ln; asm volatile("v_mbcnt_lo_u32_b32 %0, -1, 0\n\tv_mbcnt_hi_u32_b32 %0, -1, %0" : "=v"(ln)); return wv * 64 + ln; }
; __device__ __forceinline__ float shx(float v, int m, int lane) { return __int_as_float(__builtin_amdgcn_ds_bpermute((lane ^ m) << 2, __float_as_int(v))); }
; __device__ __forceinline__ unsigned xb_xcc_id() { return (unsigned)__builtin_amdgcn_s_getreg((3 << 11) | 20) & 0xFu; }
; __device__ __forceinline__ void fourier_mid_row(int wv, const Params& p) {
;     ...
;         for (int j = 0; j < 4; ++j) { const u32x4 w = *(const u32x4*)(src + j * 8);
;             acc += (bflo(w.x) - bfhi(w.x)) + (bflo(w.y) - bfhi(w.y)) + (bflo(w.z) - bfhi(w.z)) + (bflo(w.w) - bfhi(w.w)); }
; #pragma unroll
;         for (int o = 32; o >= 1; o >>= 1) acc += shx(acc, o, lane);
;         if (lane == 0) { PQ[((size_t)bt * 2048 + 1024) * 512 + ch] = f2bf(acc * 0.022097086912079608f); PQ[((size_t)bt * 2048 + 1024) * 512 + 256 + ch] = 0; } }
; __device__ __forceinline__ void grid_bar(int wv, unsigned* bar, volatile LAS unsigned* st) {
;     asm volatile("s_waitcnt vmcnt(0)" ::: "memory");
;     __syncthreads();
;     if (otid(wv) == 0) {
;         __builtin_amdgcn_s_waitcnt(0);
;         const unsigned x = xb_xcc_id();
;         unsigned nloc = st[0], nx = st[1];
;         if (nloc == 0u) { xcd_barrier_complete(bar, x, nloc, nx); st[0] = nloc; st[1] = nx; }
.LBB0_887:
	s_or_b64 exec, exec, s[6:7]
	s_waitcnt vmcnt(0)
	v_lshlrev_b32_e32 v118, 16, v192
	v_and_b32_e32 v120, 0xffff0000, v192
	v_sub_f32_e32 v118, v118, v120
	v_lshlrev_b32_e32 v119, 16, v193
	v_and_b32_e32 v120, 0xffff0000, v193
	v_sub_f32_e32 v119, v119, v120
	v_add_f32_e32 v118, v119, v118
	v_lshlrev_b32_e32 v119, 16, v194
	v_and_b32_e32 v120, 0xffff0000, v194
	v_sub_f32_e32 v119, v119, v120
	v_add_f32_e32 v118, v119, v118
	v_lshlrev_b32_e32 v119, 16, v195
	v_and_b32_e32 v120, 0xffff0000, v195
	v_sub_f32_e32 v119, v119, v120
	v_add_f32_e32 v118, v119, v118
	v_lshlrev_b32_e32 v119, 16, v188
	v_and_b32_e32 v120, 0xffff0000, v188
	v_sub_f32_e32 v119, v119, v120
	v_lshlrev_b32_e32 v121, 16, v189
	v_and_b32_e32 v120, 0xffff0000, v189
	v_sub_f32_e32 v121, v121, v120
	v_add_f32_e32 v119, v121, v119
	v_lshlrev_b32_e32 v121, 16, v190
	v_and_b32_e32 v120, 0xffff0000, v190
	v_sub_f32_e32 v121, v121, v120
	v_add_f32_e32 v119, v121, v119
	v_lshlrev_b32_e32 v121, 16, v191
	v_and_b32_e32 v120, 0xffff0000, v191
	v_sub_f32_e32 v121, v121, v120
	v_add_f32_e32 v119, v121, v119
	v_add_f32_e32 v118, 0, v118
	v_add_f32_e32 v118, v118, v119
	v_lshlrev_b32_e32 v119, 16, v184
	v_and_b32_e32 v120, 0xffff0000, v184
	v_sub_f32_e32 v119, v119, v120
	v_lshlrev_b32_e32 v121, 16, v185
	v_and_b32_e32 v120, 0xffff0000, v185
	v_sub_f32_e32 v121, v121, v120
	v_add_f32_e32 v119, v121, v119
	v_lshlrev_b32_e32 v121, 16, v186
	v_and_b32_e32 v120, 0xffff0000, v186
	v_sub_f32_e32 v121, v121, v120
	v_add_f32_e32 v119, v121, v119
	v_lshlrev_b32_e32 v121, 16, v187
	v_and_b32_e32 v120, 0xffff0000, v187
	v_sub_f32_e32 v121, v121, v120
	v_add_f32_e32 v119, v121, v119
	v_add_f32_e32 v118, v118, v119
	v_lshlrev_b32_e32 v119, 16, v180
	v_and_b32_e32 v120, 0xffff0000, v180
	v_sub_f32_e32 v119, v119, v120
	v_lshlrev_b32_e32 v121, 16, v181
	v_and_b32_e32 v120, 0xffff0000, v181
	v_sub_f32_e32 v121, v121, v120
	v_add_f32_e32 v119, v121, v119
	v_lshlrev_b32_e32 v121, 16, v182
	v_and_b32_e32 v120, 0xffff0000, v182
	v_sub_f32_e32 v121, v121, v120
	v_add_f32_e32 v119, v121, v119
	v_lshlrev_b32_e32 v121, 16, v183
	v_and_b32_e32 v120, 0xffff0000, v183
	v_sub_f32_e32 v121, v121, v120
	v_add_f32_e32 v119, v121, v119
	v_add_f32_e32 v118, v118, v119
	v_lshlrev_b32_e32 v122, 2, v176
	v_xor_b32_e32 v123, 0x80, v122
	ds_bpermute_b32 v119, v123, v118
	s_waitcnt lgkmcnt(0)
	v_add_f32_e32 v118, v118, v119
	v_xor_b32_e32 v123, 64, v122
	ds_bpermute_b32 v119, v123, v118
	s_waitcnt lgkmcnt(0)
	v_add_f32_e32 v118, v118, v119
	v_xor_b32_e32 v123, 32, v122
	ds_bpermute_b32 v119, v123, v118
	s_waitcnt lgkmcnt(0)
	v_add_f32_e32 v118, v118, v119
	v_xor_b32_e32 v123, 16, v122
	ds_bpermute_b32 v119, v123, v118
	s_waitcnt lgkmcnt(0)
	v_add_f32_e32 v118, v118, v119
	v_xor_b32_e32 v123, 8, v122
	ds_bpermute_b32 v119, v123, v118
	s_waitcnt lgkmcnt(0)
	v_add_f32_e32 v118, v118, v119
	v_xor_b32_e32 v123, 4, v122
	ds_bpermute_b32 v119, v123, v118
	s_waitcnt lgkmcnt(0)
	v_add_f32_e32 v118, v118, v119
	v_cmp_eq_u32_e32 vcc, 0, v176
	s_load_dwordx2 s[12:13], s[90:91], 0xa8
	v_mul_f32_e32 v118, 0x3cb504f3, v118
	v_bfe_u32 v119, v118, 16, 1
	v_add3_u32 v118, v118, v119, s54
	v_lshrrev_b32_e32 v124, 8, v177
	v_lshlrev_b32_e32 v124, 21, v124
	v_and_b32_e32 v125, 0xff, v177
	v_lshl_add_u32 v124, v125, 1, v124
	v_add_u32_e32 v124, 0x8820000, v124
	s_and_saveexec_b64 s[4:5], vcc
	s_waitcnt lgkmcnt(0)
	global_store_short_d16_hi v124, v118, s[12:13]
	global_store_short v124, v1, s[12:13] offset:512
	s_or_b64 exec, exec, s[4:5]
	s_mov_b64 s[4:5], s[90:91]
	s_waitcnt vmcnt(0)
	v_readlane_b32 s0, v253, 3
	s_barrier
	v_mbcnt_lo_u32_b32 v0, -1, 0
	v_mbcnt_hi_u32_b32 v0, -1, v0
	s_nop 0
	v_cmp_eq_u32_e32 vcc, s0, v0
	s_and_saveexec_b64 s[6:7], vcc
	s_cbranch_execz .LBB0_939
	v_readlane_b32 s1, v254, 63
	s_load_dwordx2 s[8:9], s[4:5], 0xa8
	s_waitcnt vmcnt(0) expcnt(0) lgkmcnt(0)
	v_mov_b32_e32 v0, s1
	s_getreg_b32 s0, hwreg(HW_REG_XCC_ID, 0, 4)
	ds_read_b32 v3, v0
	v_readlane_b32 s1, v255, 0
	s_and_b32 s0, s0, 15
	s_waitcnt lgkmcnt(0)
	v_cmp_ne_u32_e32 vcc, 0, v3
	v_mov_b32_e32 v0, s1
	ds_read_b32 v2, v0
	s_cbranch_vccnz .LBB0_903
	s_add_u32 s10, s8, 0xfab9b00
	s_addc_u32 s11, s9, 0
	s_add_u32 s12, s8, 0xfab9d00
	s_addc_u32 s13, s9, 0
	s_add_u32 s14, s8, 0xfab9e00
	s_addc_u32 s15, s9, 0
	s_add_u32 s16, s8, 0xfab9f00
	s_addc_u32 s17, s9, 0
	s_add_u32 s18, s8, 0xfaba000
	s_addc_u32 s19, s9, 0
	s_add_u32 s20, s8, 0xfaba100
	s_addc_u32 s21, s9, 0
	s_add_u32 s22, s8, 0xfaba200
	s_addc_u32 s23, s9, 0
	s_add_u32 s24, s8, 0xfaba300
	s_addc_u32 s25, s9, 0
	s_add_u32 s26, s8, 0xfaba400
	s_addc_u32 s27, s9, 0
	s_add_u32 s28, s8, 0xfaba500
	s_addc_u32 s29, s9, 0
	s_add_u32 s30, s8, 0xfaba600
	s_addc_u32 s31, s9, 0
	s_add_u32 s34, s8, 0xfaba700
	s_addc_u32 s35, s9, 0
	s_add_u32 s36, s8, 0xfaba800
	s_addc_u32 s37, s9, 0
	s_add_u32 s38, s8, 0xfaba900
	s_addc_u32 s39, s9, 0
	s_add_u32 s40, s8, 0xfabaa00
	s_addc_u32 s41, s9, 0
	s_add_u32 s42, s8, 0xfabab00
	s_addc_u32 s43, s9, 0
	s_add_u32 s48, s8, 0xfabac00
	s_addc_u32 s49, s9, 0
	s_mov_b32 s1, 1
	s_branch .LBB0_891
